# stack: previous best plus early first PV0 MFMA and Q fragment prefetch in front of the tile barrier
# speedup vs baseline: 1.0090x; 1.0069x over previous
; #define LAS __attribute__((address_space(3)))
; __device__ __forceinline__ void dattn_unit(LAS unsigned char* lds, int b, int h, int qb, const bf16* Q, const bf16* K, const bf16* V, bf16* YB, float lam, const float* subg, float oml, int tid) {
;     ...
;             for (int cb = 0; cb < 4; ++cb) { const LAS bf16* vp = Vt + (32 * cb + ql) * 72 + 32 * sub + 4 * hi;
;                 const v2u a0 = *(const LAS v2u*)(vp), a1 = *(const LAS v2u*)(vp + 8), a2 = *(const LAS v2u*)(vp + 16), a3 = *(const LAS v2u*)(vp + 24);
;                 const v4u f0 = {a0.x, a0.y, a1.x, a1.y}, f1 = {a2.x, a2.y, a3.x, a3.y};
;                 o[0][cb] = __builtin_amdgcn_mfma_f32_32x32x16_bf16(__builtin_bit_cast(bf16x8, f0), pA0, o[0][cb], 0, 0, 0);
;                 o[1][cb] = __builtin_amdgcn_mfma_f32_32x32x16_bf16(__builtin_bit_cast(bf16x8, f0), pA1, o[1][cb], 0, 0, 0);
;                 o[0][cb] = __builtin_amdgcn_mfma_f32_32x32x16_bf16(__builtin_bit_cast(bf16x8, f1), pB0, o[0][cb], 0, 0, 0);
;                 o[1][cb] = __builtin_amdgcn_mfma_f32_32x32x16_bf16(__builtin_bit_cast(bf16x8, f1), pB1, o[1][cb], 0, 0, 0); }
.LBB0_232:
	v_cvt_pk_bf16_f32 v224, v201, v202
	v_cvt_pk_bf16_f32 v225, v203, v204
	v_cvt_pk_bf16_f32 v226, v205, v206
	v_cvt_pk_bf16_f32 v227, v207, v218
	ds_read_b128 v[204:207], v219 offset:18464
	ds_read_b128 v[200:203], v219 offset:32288
	v_cvt_pk_bf16_f32 v148, v147, v148
	v_cvt_pk_bf16_f32 v149, v149, v150
	s_waitcnt lgkmcnt(2)
	v_mfma_f32_32x32x16_bf16 v[80:95], v[228:231], v[224:227], v[80:95]
	v_cvt_pk_bf16_f32 v150, v151, v152
	v_cvt_pk_bf16_f32 v151, v153, v154
	v_add_f32_e32 v179, v179, v145
	v_exp_f32_e32 v155, v128
	v_exp_f32_e32 v129, v129
	v_exp_f32_e32 v130, v130
	v_exp_f32_e32 v131, v131
	v_exp_f32_e32 v132, v132
	v_add_f32_e32 v128, v129, v155
	v_exp_f32_e32 v156, v133
	v_mfma_f32_32x32x16_bf16 v[80:95], v[232:235], v[148:151], v[80:95]
	v_add_f32_e32 v128, v130, v128
	v_exp_f32_e32 v157, v134
	v_add_f32_e32 v128, v131, v128
	v_exp_f32_e32 v158, v135
	v_mfma_f32_32x32x16_bf16 v[48:63], v[236:239], v[224:227], v[48:63]
	v_add_f32_e32 v128, v132, v128
	v_exp_f32_e32 v133, v136
	v_add_f32_e32 v128, v156, v128
	v_exp_f32_e32 v134, v137
	v_mfma_f32_32x32x16_bf16 v[48:63], v[240:243], v[148:151], v[48:63]
	v_add_f32_e32 v128, v157, v128
	v_exp_f32_e32 v135, v138
	v_add_f32_e32 v128, v158, v128
	v_exp_f32_e32 v136, v139
	v_mfma_f32_32x32x16_bf16 v[16:31], v[212:215], v[224:227], v[16:31]
	v_add_f32_e32 v128, v133, v128
	v_exp_f32_e32 v137, v140
	v_add_f32_e32 v128, v134, v128
	v_exp_f32_e32 v138, v141
	v_mfma_f32_32x32x16_bf16 v[112:127], v[220:223], v[224:227], v[112:127]
	v_add_f32_e32 v128, v135, v128
	v_exp_f32_e32 v139, v142
	v_add_f32_e32 v128, v136, v128
	v_exp_f32_e32 v140, v143
	s_waitcnt lgkmcnt(1)
	v_mfma_f32_32x32x16_bf16 v[112:127], v[204:207], v[148:151], v[112:127]
	v_add_f32_e32 v128, v137, v128
	v_add_f32_e32 v128, v138, v128
	v_add_f32_e32 v128, v139, v128
	v_add_f32_e32 v128, v140, v128
	s_waitcnt lgkmcnt(0)
	v_mfma_f32_32x32x16_bf16 v[16:31], v[200:203], v[148:151], v[16:31]
	v_cmp_lt_f32_e32 vcc, s82, v128
	s_mov_b64 s[46:47], 0
	s_cbranch_vccz .LBB0_234
	s_mov_b64 s[46:47], -1
	v_max_f32_e32 v141, v131, v131
	v_max_f32_e32 v142, v130, v130
	v_max_f32_e32 v141, v142, v141
	v_max_f32_e32 v142, v158, v158
	v_max_f32_e32 v143, v157, v157
	v_max_f32_e32 v142, v143, v142
	v_max_f32_e32 v143, v134, v134
	v_max_f32_e32 v144, v133, v133
	v_max_f32_e32 v143, v144, v143
	v_max_f32_e32 v144, v136, v136
	v_max_f32_e32 v159, v135, v135
	v_max_f32_e32 v144, v159, v144
	v_max_f32_e32 v159, v140, v140
	v_max_f32_e32 v147, v139, v139
	v_max_f32_e32 v159, v147, v159
	v_max3_f32 v159, v137, v138, v159
	v_max3_f32 v141, v155, v129, v141
	v_max3_f32 v142, v132, v156, v142
	v_max3_f32 v143, v143, v144, v159
	v_max3_f32 v141, v141, v142, v143
	v_mov_b32_e32 v142, v141
	s_nop 1
	v_permlane32_swap_b32_e32 v141, v142
	v_max_f32_e32 v142, v142, v142
	v_max_f32_e32 v141, v141, v141
	v_max_f32_e32 v144, v141, v142

; #define LAS __attribute__((address_space(3)))
; __device__ __forceinline__ void dattn_unit(LAS unsigned char* lds, int b, int h, int qb, const bf16* Q, const bf16* K, const bf16* V, bf16* YB, float lam, const float* subg, float oml, int tid) {
;     ...
;             for (int cb = 0; cb < 4; ++cb) { const LAS bf16* vp = Vt + (32 * cb + ql) * 72 + 32 * sub + 4 * hi;
;                 const v2u a0 = *(const LAS v2u*)(vp), a1 = *(const LAS v2u*)(vp + 8), a2 = *(const LAS v2u*)(vp + 16), a3 = *(const LAS v2u*)(vp + 24);
;                 const v4u f0 = {a0.x, a0.y, a1.x, a1.y}, f1 = {a2.x, a2.y, a3.x, a3.y};
;                 o[0][cb] = __builtin_amdgcn_mfma_f32_32x32x16_bf16(__builtin_bit_cast(bf16x8, f0), pA0, o[0][cb], 0, 0, 0);
;                 o[1][cb] = __builtin_amdgcn_mfma_f32_32x32x16_bf16(__builtin_bit_cast(bf16x8, f0), pA1, o[1][cb], 0, 0, 0);
;                 o[0][cb] = __builtin_amdgcn_mfma_f32_32x32x16_bf16(__builtin_bit_cast(bf16x8, f1), pB0, o[0][cb], 0, 0, 0);
;                 o[1][cb] = __builtin_amdgcn_mfma_f32_32x32x16_bf16(__builtin_bit_cast(bf16x8, f1), pB1, o[1][cb], 0, 0, 0); }
.LBB0_243:
	v_cvt_pk_bf16_f32 v205, v205, v206
	v_cvt_pk_bf16_f32 v206, v207, v218
	v_cvt_pk_bf16_f32 v207, v219, v220
	v_cvt_pk_bf16_f32 v204, v199, v204
	ds_read_b128 v[218:221], v243 offset:32352
	v_cvt_pk_bf16_f32 v148, v147, v148
	v_cvt_pk_bf16_f32 v149, v149, v150
	s_waitcnt lgkmcnt(1)
	v_mfma_f32_32x32x16_bf16 v[80:95], v[222:225], v[204:207], v[80:95]
	v_cvt_pk_bf16_f32 v150, v151, v152
	v_cvt_pk_bf16_f32 v151, v153, v154
	v_add_f32_e32 v179, v179, v145
	v_exp_f32_e32 v155, v128
	v_exp_f32_e32 v129, v129
	v_exp_f32_e32 v130, v130
	v_exp_f32_e32 v131, v131
	v_exp_f32_e32 v132, v132
	v_add_f32_e32 v128, v129, v155
	v_exp_f32_e32 v156, v133
	v_mfma_f32_32x32x16_bf16 v[80:95], v[226:229], v[148:151], v[80:95]
	v_add_f32_e32 v128, v130, v128
	v_exp_f32_e32 v157, v134
	v_add_f32_e32 v128, v131, v128
	v_exp_f32_e32 v158, v135
	v_mfma_f32_32x32x16_bf16 v[48:63], v[230:233], v[204:207], v[48:63]
	v_add_f32_e32 v128, v132, v128
	v_exp_f32_e32 v133, v136
	v_add_f32_e32 v128, v156, v128
	v_exp_f32_e32 v134, v137
	v_mfma_f32_32x32x16_bf16 v[48:63], v[234:237], v[148:151], v[48:63]
	v_add_f32_e32 v128, v157, v128
	v_exp_f32_e32 v135, v138
	v_add_f32_e32 v128, v158, v128
	v_exp_f32_e32 v136, v139
	v_mfma_f32_32x32x16_bf16 v[16:31], v[238:241], v[204:207], v[16:31]
	v_add_f32_e32 v128, v133, v128
	v_exp_f32_e32 v137, v140
	v_add_f32_e32 v128, v134, v128
	v_exp_f32_e32 v138, v141
	v_mfma_f32_32x32x16_bf16 v[112:127], v[212:215], v[204:207], v[112:127]
	v_add_f32_e32 v128, v135, v128
	v_exp_f32_e32 v139, v142
	v_add_f32_e32 v128, v136, v128
	v_exp_f32_e32 v140, v143
	v_mfma_f32_32x32x16_bf16 v[112:127], v[200:203], v[148:151], v[112:127]
	v_add_f32_e32 v128, v137, v128
	v_add_f32_e32 v128, v138, v128
	v_add_f32_e32 v128, v139, v128
	v_add_f32_e32 v128, v140, v128
	s_waitcnt lgkmcnt(0)
	v_mfma_f32_32x32x16_bf16 v[16:31], v[218:221], v[148:151], v[16:31]
	v_cmp_lt_f32_e32 vcc, s82, v128
	s_mov_b64 s[46:47], 0
	s_cbranch_vccz .LBB0_245
	s_mov_b64 s[46:47], -1
	v_max_f32_e32 v141, v131, v131
	v_max_f32_e32 v142, v130, v130
	v_max_f32_e32 v141, v142, v141
	v_max_f32_e32 v142, v158, v158
	v_max_f32_e32 v143, v157, v157
	v_max_f32_e32 v142, v143, v142
	v_max_f32_e32 v143, v134, v134
	v_max_f32_e32 v144, v133, v133
	v_max_f32_e32 v143, v144, v143
	v_max_f32_e32 v144, v136, v136
	v_max_f32_e32 v159, v135, v135
	v_max_f32_e32 v144, v159, v144
	v_max_f32_e32 v159, v140, v140
	v_max_f32_e32 v147, v139, v139
	v_max_f32_e32 v159, v147, v159
	v_max3_f32 v159, v137, v138, v159
	v_max3_f32 v141, v155, v129, v141
	v_max3_f32 v142, v132, v156, v142
	v_max3_f32 v143, v143, v144, v159
	v_max3_f32 v141, v141, v142, v143
	v_mov_b32_e32 v142, v141
	s_nop 1
	v_permlane32_swap_b32_e32 v141, v142
	v_max_f32_e32 v142, v142, v142
	v_max_f32_e32 v141, v141, v141
	v_max_f32_e32 v144, v141, v142
